# v21 + packed v_pk_fma_f32 in the dense softmax split into scalar v_fma pairs; LDS-buffer toggle XORs moved ahead of the tile barriers (off the post-barrier path)
# speedup vs baseline: 1.0046x; 1.0015x over previous
; #define SBAR() __builtin_amdgcn_sched_barrier(0)
; __device__ __forceinline__ void partialSM(f32x16& p0, f32x16& p1, float& m_reg, float& mn, float& alpha) {
;     ...
;   float mnC = -mn * C;
; #pragma unroll
;   for (int r = 0; r < 16; ++r) p0[r] = fmaf(p0[r], C, mnC);
; #pragma unroll
;   for (int r = 0; r < 16; ++r) p1[r] = fmaf(p1[r], C, mnC);
; #pragma unroll
;   for (int r = 0; r < 16; ++r) p0[r] = __builtin_amdgcn_exp2f(p0[r]);
; }
; __device__ __forceinline__ void finishSM(f32x16& p0, f32x16& p1, float alpha, float& l_reg, bf16x8& pa0, bf16x8& pa1, bf16x8& pa2, bf16x8& pa3) {
; #pragma unroll
;   for (int r = 0; r < 16; ++r) p1[r] = __builtin_amdgcn_exp2f(p1[r]);
;   float ps = 0;
; #pragma unroll
;   for (int r = 0; r < 16; ++r) ps += p0[r];
; #pragma unroll
;   for (int r = 0; r < 16; ++r) ps += p1[r];
;   { auto rr = __builtin_amdgcn_permlane32_swap(__float_as_uint(ps), __float_as_uint(ps), false, false);
;     ps = __uint_as_float(rr[0]) + __uint_as_float(rr[1]); }
;   l_reg = l_reg * alpha + ps;
;   PK4(p0, 0, pa0); PK4(p0, 8, pa1); PK4(p1, 0, pa2); PK4(p1, 8, pa3);
; }
;   p0 = f32x16{}; p1 = f32x16{};
; #pragma unroll
;   for (int d0 = DLO; d0 < DHI; ++d0) { int cb = (d0 * 16 + hi * 8) * 2;
;     bf16x8 b0 = *reinterpret_cast<const bf16x8*>((const char*)Ks + KSWZ(r32, cb));
;     bf16x8 b1 = *reinterpret_cast<const bf16x8*>((const char*)Ks + KSWZ(32 + r32, cb));
; template <int DLO, int DHI>
; __device__ __forceinline__ void attn_dense_body(const int g_wave, const bf16* __restrict__ Qb, const bf16* __restrict__ Kh, const bf16* __restrict__ Vh,
;                                                 bf16* __restrict__ Ob, int ldo, char* lds) {
;     ...
;     SBAR(); qkt<DLO, DHI>(pB0, pB1, (bf16*)((char*)K_lds + SHM_K), qr, r32, hi);
;     finishSM(pA0, pA1, alA, l_reg, pa0, pa1, pa2, pa3); SBAR();
;     SLOAD(SO, (j + 2) * KVBLK); SBAR();
;     pv_d0(o, vb0, pa0, pa1, pa2, pa3); partialSM(pB0, pB1, m_reg, mnB, alB);
;     __syncthreads(); SWAIT(); SWRITE(0, SE);
;     RESC(alB); __syncthreads();
;     SBAR(); qkt<DLO, DHI>(pA0, pA1, K_lds, qr, r32, hi);
;     finishSM(pB0, pB1, alB, l_reg, pa0, pa1, pa2, pa3); SBAR();
;     if (j + 3 < NT) SLOAD(SE, (j + 3) * KVBLK); SBAR();
;     pv_d0(o, vb0 + (int)SHM_V, pa0, pa1, pa2, pa3); partialSM(pA0, pA1, m_reg, mnA, alA);
;     __syncthreads(); SWAIT(); SWRITE(1, SO);
;     RESC(alA); __syncthreads();
.LBB0_1006:
	v_cndmask_b32_e64 v210, v146, v150, s[8:9]
	v_mul_f32_e32 v211, 0xbe0293ee, v210
	v_fmamk_f32 v82, v82, 0x3e0293ee, v211
	v_fmamk_f32 v83, v83, 0x3e0293ee, v211
	v_fmamk_f32 v84, v84, 0x3e0293ee, v211
	v_fmamk_f32 v85, v85, 0x3e0293ee, v211
	v_fmamk_f32 v86, v86, 0x3e0293ee, v211
	v_fmamk_f32 v87, v87, 0x3e0293ee, v211
	v_fmamk_f32 v88, v88, 0x3e0293ee, v211
	v_fmamk_f32 v89, v89, 0x3e0293ee, v211
	v_fmamk_f32 v90, v90, 0x3e0293ee, v211
	v_fmamk_f32 v91, v91, 0x3e0293ee, v211
	v_fmamk_f32 v92, v92, 0x3e0293ee, v211
	v_fmamk_f32 v93, v93, 0x3e0293ee, v211
	v_fmamk_f32 v94, v94, 0x3e0293ee, v211
	v_fmamk_f32 v95, v95, 0x3e0293ee, v211
	v_fmamk_f32 v96, v96, 0x3e0293ee, v211
	v_fmamk_f32 v97, v97, 0x3e0293ee, v211
	v_exp_f32_e32 v146, v82
	v_exp_f32_e32 v161, v83
	v_exp_f32_e32 v147, v84
	v_exp_f32_e32 v160, v85
	v_exp_f32_e32 v148, v86
	v_exp_f32_e32 v159, v87
	v_exp_f32_e32 v149, v88
	v_exp_f32_e32 v158, v89
	v_exp_f32_e32 v150, v90
	v_exp_f32_e32 v157, v91
	v_exp_f32_e32 v151, v92
	v_exp_f32_e32 v156, v93
	v_exp_f32_e32 v152, v94
	v_exp_f32_e32 v155, v95
	v_exp_f32_e32 v153, v96
	v_exp_f32_e32 v154, v97
	v_fmamk_f32 v220, v66, 0x3e0293ee, v211
	v_fmamk_f32 v221, v67, 0x3e0293ee, v211
	v_fmamk_f32 v222, v68, 0x3e0293ee, v211
	v_fmamk_f32 v223, v69, 0x3e0293ee, v211
	v_fmamk_f32 v224, v70, 0x3e0293ee, v211
	v_fmamk_f32 v213, v71, 0x3e0293ee, v211
	v_fmamk_f32 v214, v72, 0x3e0293ee, v211
	v_fmamk_f32 v215, v73, 0x3e0293ee, v211
	v_fmamk_f32 v216, v74, 0x3e0293ee, v211
	v_fmamk_f32 v217, v75, 0x3e0293ee, v211
	v_fmamk_f32 v218, v76, 0x3e0293ee, v211
	v_fmamk_f32 v219, v77, 0x3e0293ee, v211
	v_fmamk_f32 v212, v78, 0x3e0293ee, v211
	v_fmamk_f32 v225, v79, 0x3e0293ee, v211
	v_fmamk_f32 v226, v80, 0x3e0293ee, v211
	v_fmac_f32_e32 v211, 0x3e0293ee, v81
	v_xor_b32_e32 v190, 0x10000, v190
	v_xor_b32_e32 v194, 0x10000, v194
	v_xor_b32_e32 v195, 0x10000, v195
	v_xor_b32_e32 v196, 0x10000, v196
	s_waitcnt lgkmcnt(0)
	s_barrier
	ds_read_b128 v[66:69], v190 offset:32768
	ds_read_b128 v[70:73], v190 offset:40960
	ds_read_b128 v[232:235], v194 offset:32768
	ds_read_b128 v[236:239], v194 offset:40960
	ds_read_b128 v[240:243], v195 offset:32768
	ds_read_b128 v[244:247], v195 offset:40960
	ds_read_b128 v[248:251], v196 offset:32768
	ds_read_b128 v[114:117], v196 offset:40960
	v_exp_f32_e32 v213, v213
	v_exp_f32_e32 v214, v214
	s_waitcnt lgkmcnt(7)
	v_mfma_f32_32x32x16_bf16 v[82:97], v[66:69], v[102:105], 0
	v_exp_f32_e32 v215, v215
	v_exp_f32_e32 v216, v216
	v_exp_f32_e32 v217, v217
	v_exp_f32_e32 v218, v218
	v_exp_f32_e32 v219, v219
	s_waitcnt lgkmcnt(6)
	v_mfma_f32_32x32x16_bf16 v[66:81], v[70:73], v[102:105], 0
	s_waitcnt lgkmcnt(5)
	v_mfma_f32_32x32x16_bf16 v[82:97], v[232:235], v[98:101], v[82:97]
	s_waitcnt lgkmcnt(4)
	v_mfma_f32_32x32x16_bf16 v[66:81], v[236:239], v[98:101], v[66:81]
	s_waitcnt lgkmcnt(3)
	v_mfma_f32_32x32x16_bf16 v[82:97], v[240:243], v[106:109], v[82:97]
	s_waitcnt lgkmcnt(2)
	v_mfma_f32_32x32x16_bf16 v[66:81], v[244:247], v[106:109], v[66:81]
	s_waitcnt lgkmcnt(1)
	v_mfma_f32_32x32x16_bf16 v[82:97], v[248:251], v[110:113], v[82:97]
	v_exp_f32_e32 v186, v220
	v_exp_f32_e32 v220, v224
	v_exp_f32_e32 v224, v211
	v_add_f32_e32 v211, 0, v146
	v_add_f32_e32 v211, v161, v211
	v_add_f32_e32 v211, v147, v211
	v_add_f32_e32 v211, v160, v211
	v_add_f32_e32 v211, v148, v211
	v_add_f32_e32 v211, v159, v211
	v_add_f32_e32 v211, v149, v211
	v_add_f32_e32 v211, v158, v211
	v_add_f32_e32 v211, v150, v211
	v_add_f32_e32 v211, v157, v211
	v_add_f32_e32 v211, v151, v211
	v_add_f32_e32 v211, v156, v211
	v_add_f32_e32 v211, v152, v211
	v_exp_f32_e32 v187, v221
	v_add_f32_e32 v211, v155, v211
	v_exp_f32_e32 v188, v222
	v_add_f32_e32 v211, v153, v211
	v_exp_f32_e32 v189, v223
	v_add_f32_e32 v211, v154, v211
	v_add_f32_e32 v211, v186, v211
	v_add_f32_e32 v211, v187, v211
	v_add_f32_e32 v211, v188, v211
	v_add_f32_e32 v211, v189, v211
	v_add_f32_e32 v211, v220, v211
	v_add_f32_e32 v211, v213, v211
	v_add_f32_e32 v211, v214, v211
	v_add_f32_e32 v211, v215, v211
	v_exp_f32_e32 v221, v212
	v_add_f32_e32 v211, v216, v211
	v_exp_f32_e32 v222, v225
	v_add_f32_e32 v211, v217, v211
	s_waitcnt lgkmcnt(0)
	v_mfma_f32_32x32x16_bf16 v[66:81], v[114:117], v[110:113], v[66:81]
	v_exp_f32_e32 v223, v226
	v_add_f32_e32 v211, v218, v211
	v_add_f32_e32 v211, v219, v211
	v_add_f32_e32 v211, v221, v211
	v_add_f32_e32 v211, v222, v211
	v_add_f32_e32 v211, v223, v211
	v_add_f32_e32 v211, v224, v211
	v_mov_b32_e32 v212, v211
	v_cvt_pk_bf16_f32 v146, v146, v161
	v_cvt_pk_bf16_f32 v147, v147, v160
	v_cvt_pk_bf16_f32 v148, v148, v159
	v_cvt_pk_bf16_f32 v149, v149, v158
	v_cvt_pk_bf16_f32 v150, v150, v157
	v_cvt_pk_bf16_f32 v151, v151, v156
	v_cvt_pk_bf16_f32 v152, v152, v155
	v_cvt_pk_bf16_f32 v153, v153, v154
	v_cvt_pk_bf16_f32 v154, v186, v187
	v_cvt_pk_bf16_f32 v155, v188, v189
	v_cvt_pk_bf16_f32 v156, v220, v213
	v_cvt_pk_bf16_f32 v157, v214, v215
	v_cvt_pk_bf16_f32 v158, v216, v217
	v_cvt_pk_bf16_f32 v159, v218, v219
	v_cvt_pk_bf16_f32 v160, v221, v222
	v_cvt_pk_bf16_f32 v161, v223, v224
	s_nop 1
	v_permlane32_swap_b32_e32 v211, v212
	v_permlane32_swap_b32_e32 v146, v148
	v_permlane32_swap_b32_e32 v147, v149
	v_permlane32_swap_b32_e32 v150, v152
	v_permlane32_swap_b32_e32 v151, v153
	v_permlane32_swap_b32_e32 v154, v156
	v_permlane32_swap_b32_e32 v155, v157
	v_permlane32_swap_b32_e32 v158, v160
	v_permlane32_swap_b32_e32 v159, v161
	s_waitcnt vmcnt(0)
	ds_write_b128 v192, v[130:133] offset:16384
	ds_write_b128 v193, v[134:137] offset:16384
	ds_write_b128 v177, v[138:141] offset:49152
	ds_write_b128 v191, v[142:145] offset:49152
	s_cmp_gt_u32 s34, 60
	s_cselect_b64 s[2:3], -1, 0
	s_and_b64 vcc, exec, s[2:3]
	s_cbranch_vccnz .LBB0_1008
	v_add_co_u32_e32 v114, vcc, 0x19040000, v168
	s_nop 1
	v_addc_co_u32_e32 v115, vcc, 0, v169, vcc
	v_add_co_u32_e32 v118, vcc, 0x19088000, v168
	s_nop 1
	v_addc_co_u32_e32 v119, vcc, 0, v169, vcc
	v_add_co_u32_e32 v122, vcc, 0x1f660000, v166
	global_load_dwordx4 v[114:117], v[114:115], off
	s_nop 0
	global_load_dwordx4 v[118:121], v[118:119], off
	v_addc_co_u32_e32 v123, vcc, 0, v167, vcc
	v_add_co_u32_e32 v126, vcc, 0x1f66c000, v166
	s_nop 1
	v_addc_co_u32_e32 v127, vcc, 0, v167, vcc
	global_load_dwordx4 v[122:125], v[122:123], off
	s_nop 0
	global_load_dwordx4 v[126:129], v[126:127], off

; #define SWRITE(b, i) do { *(bf16x8*)((char*)V_lds + (b) * SHM_V + vst0) = sr_[i].vs0;          \
;     *(bf16x8*)((char*)V_lds + (b) * SHM_V + vst1) = sr_[i].vs1; int kc = sc * 2;               \
;     *(bf16x8*)((char*)K_lds + (b) * SHM_K + KSWZ(sr, kc)) = sr_[i].ks0;                       \
;     *(bf16x8*)((char*)K_lds + (b) * SHM_K + KSWZ(32 + sr, kc)) = sr_[i].ks1; } while (0)
; #define SWAIT() asm volatile("s_waitcnt vmcnt(4)" ::: "memory")
; #define RESC(a) do { if (__any((a) < 1.f)) { if (hi == 0) al_l[r32] = (a); asm volatile("s_waitcnt lgkmcnt(0)" ::: "memory"); \
;     _Pragma("unroll") for (int d = 0; d < 4; ++d) _Pragma("unroll") for (int r = 0; r < 16; ++r) o[d][r] *= al_l[crow(r, hi)]; } } while (0)
; __device__ __forceinline__ void partialSM(f32x16& p0, f32x16& p1, float& m_reg, float& mn, float& alpha) {
;     ...
;   else { mn = fmaxf(m_reg, pmax); alpha = __builtin_amdgcn_exp2f((m_reg - mn) * C); m_reg = mn; }
;   float mnC = -mn * C;
; #pragma unroll
;   for (int r = 0; r < 16; ++r) p0[r] = fmaf(p0[r], C, mnC);
; #pragma unroll
;   for (int r = 0; r < 16; ++r) p1[r] = fmaf(p1[r], C, mnC);
; #pragma unroll
;   for (int r = 0; r < 16; ++r) p0[r] = __builtin_amdgcn_exp2f(p0[r]);
; template <int DLO, int DHI>
; __device__ __forceinline__ void attn_dense_body(const int g_wave, const bf16* __restrict__ Qb, const bf16* __restrict__ Kh, const bf16* __restrict__ Vh,
;                                                 bf16* __restrict__ Ob, int ldo, char* lds) {
;     ...
;     pv_d0(o, vb0 + (int)SHM_V, pa0, pa1, pa2, pa3); partialSM(pA0, pA1, m_reg, mnA, alA);
;     __syncthreads(); SWAIT(); SWRITE(1, SO);
;     RESC(alA); __syncthreads();
.LBB0_1012:
	v_cndmask_b32_e64 v150, v147, v210, s[8:9]
	v_mul_f32_e32 v136, 0xbe0293ee, v150
	v_mov_b32_e32 v137, v136
	v_fmamk_f32 v82, v82, 0x3e0293ee, v136
	v_fmamk_f32 v83, v83, 0x3e0293ee, v136
	v_fmamk_f32 v84, v84, 0x3e0293ee, v136
	v_fmamk_f32 v85, v85, 0x3e0293ee, v136
	v_fmamk_f32 v86, v86, 0x3e0293ee, v136
	v_fmamk_f32 v87, v87, 0x3e0293ee, v136
	v_fmamk_f32 v88, v88, 0x3e0293ee, v136
	v_fmamk_f32 v89, v89, 0x3e0293ee, v136
	v_fmamk_f32 v90, v90, 0x3e0293ee, v136
	v_fmamk_f32 v91, v91, 0x3e0293ee, v136
	v_fmamk_f32 v92, v92, 0x3e0293ee, v136
	v_fmamk_f32 v93, v93, 0x3e0293ee, v136
	v_fmamk_f32 v94, v94, 0x3e0293ee, v136
	v_fmamk_f32 v95, v95, 0x3e0293ee, v136
	v_fmamk_f32 v96, v96, 0x3e0293ee, v136
	v_fmac_f32_e32 v137, 0x3e0293ee, v97
	v_exp_f32_e32 v161, v82
	v_exp_f32_e32 v167, v83
	v_exp_f32_e32 v147, v84
	v_exp_f32_e32 v166, v85
	v_exp_f32_e32 v148, v86
	v_exp_f32_e32 v160, v87
	v_exp_f32_e32 v149, v88
	v_exp_f32_e32 v159, v89
	v_exp_f32_e32 v156, v90
	v_exp_f32_e32 v158, v91
	v_exp_f32_e32 v154, v92
	v_exp_f32_e32 v157, v93
	v_exp_f32_e32 v152, v94
	v_exp_f32_e32 v155, v95
	v_exp_f32_e32 v151, v96
	v_exp_f32_e32 v153, v137
	v_fma_f32 v142, v66, s62, v136
	v_fma_f32 v143, v67, s62, v136
	v_add_f32_e32 v66, v207, v208
	s_mov_b64 s[4:5], 0x30000
	v_fmac_f32_e32 v66, v197, v174
	v_add_f32_e32 v174, v211, v212
	v_lshl_add_u64 v[162:163], v[162:163], 0, s[4:5]
	s_mov_b64 s[4:5], 0x120000
	v_fma_f32 v140, v68, s62, v136
	v_fma_f32 v141, v69, s62, v136
	v_fma_f32 v134, v70, s62, v136
	v_fma_f32 v135, v71, s62, v136
	v_fma_f32 v132, v72, s62, v136
	v_fma_f32 v133, v73, s62, v136
	v_fma_f32 v130, v74, s62, v136
	v_fma_f32 v131, v75, s62, v136
	v_fma_f32 v144, v76, s62, v136
	v_fma_f32 v145, v77, s62, v136
	v_fma_f32 v138, v78, s62, v136
	v_fma_f32 v139, v79, s62, v136
	v_fma_f32 v137, v81, s62, v136
	v_fma_f32 v136, v80, s62, v136
	v_fmac_f32_e32 v174, v66, v209
	s_add_i32 s34, s34, 2
	v_lshl_add_u64 v[164:165], v[164:165], 0, s[4:5]
	s_and_b64 vcc, exec, s[2:3]
	v_xor_b32_e32 v176, 0x10000, v176
	v_xor_b32_e32 v175, 0x10000, v175
	v_xor_b32_e32 v192, 0x10000, v192
	v_xor_b32_e32 v193, 0x10000, v193
	v_xor_b32_e32 v177, 0x10000, v177
	v_xor_b32_e32 v191, 0x10000, v191
	s_waitcnt lgkmcnt(0)
	s_barrier
	s_cbranch_vccnz .LBB0_1014
	v_mov_b32_e32 v197, v146
	s_branch .LBB0_1002

; #define SBAR() __builtin_amdgcn_sched_barrier(0)
; __device__ __forceinline__ void partialSM(f32x16& p0, f32x16& p1, float& m_reg, float& mn, float& alpha) {
;     ...
;   float mnC = -mn * C;
; #pragma unroll
;   for (int r = 0; r < 16; ++r) p0[r] = fmaf(p0[r], C, mnC);
; #pragma unroll
;   for (int r = 0; r < 16; ++r) p1[r] = fmaf(p1[r], C, mnC);
; #pragma unroll
;   for (int r = 0; r < 16; ++r) p0[r] = __builtin_amdgcn_exp2f(p0[r]);
; }
; __device__ __forceinline__ void finishSM(f32x16& p0, f32x16& p1, float alpha, float& l_reg, bf16x8& pa0, bf16x8& pa1, bf16x8& pa2, bf16x8& pa3) {
; #pragma unroll
;   for (int r = 0; r < 16; ++r) p1[r] = __builtin_amdgcn_exp2f(p1[r]);
;   float ps = 0;
; #pragma unroll
;   for (int r = 0; r < 16; ++r) ps += p0[r];
; #pragma unroll
;   for (int r = 0; r < 16; ++r) ps += p1[r];
;   { auto rr = __builtin_amdgcn_permlane32_swap(__float_as_uint(ps), __float_as_uint(ps), false, false);
;     ps = __uint_as_float(rr[0]) + __uint_as_float(rr[1]); }
;   l_reg = l_reg * alpha + ps;
;   PK4(p0, 0, pa0); PK4(p0, 8, pa1); PK4(p1, 0, pa2); PK4(p1, 8, pa3);
; }
;   p0 = f32x16{}; p1 = f32x16{};
; #pragma unroll
;   for (int d0 = DLO; d0 < DHI; ++d0) { int cb = (d0 * 16 + hi * 8) * 2;
;     bf16x8 b0 = *reinterpret_cast<const bf16x8*>((const char*)Ks + KSWZ(r32, cb));
;     bf16x8 b1 = *reinterpret_cast<const bf16x8*>((const char*)Ks + KSWZ(32 + r32, cb));
; template <int DLO, int DHI>
; __device__ __forceinline__ void attn_dense_body(const int g_wave, const bf16* __restrict__ Qb, const bf16* __restrict__ Kh, const bf16* __restrict__ Vh,
;                                                 bf16* __restrict__ Ob, int ldo, char* lds) {
;     ...
;     SBAR(); qkt<DLO, DHI>(pB0, pB1, (bf16*)((char*)K_lds + SHM_K), qr, r32, hi);
;     finishSM(pA0, pA1, alA, l_reg, pa0, pa1, pa2, pa3); SBAR();
;     SLOAD(SO, (j + 2) * KVBLK); SBAR();
;     pv_d0(o, vb0, pa0, pa1, pa2, pa3); partialSM(pB0, pB1, m_reg, mnB, alB);
;     __syncthreads(); SWAIT(); SWRITE(0, SE);
;     RESC(alB); __syncthreads();
;     SBAR(); qkt<DLO, DHI>(pA0, pA1, K_lds, qr, r32, hi);
;     finishSM(pB0, pB1, alB, l_reg, pa0, pa1, pa2, pa3); SBAR();
;     if (j + 3 < NT) SLOAD(SE, (j + 3) * KVBLK); SBAR();
;     pv_d0(o, vb0 + (int)SHM_V, pa0, pa1, pa2, pa3); partialSM(pA0, pA1, m_reg, mnA, alA);
;     __syncthreads(); SWAIT(); SWRITE(1, SO);
;     RESC(alA); __syncthreads();
.LBB0_1026:
	v_cndmask_b32_e64 v210, v146, v150, s[8:9]
	v_mul_f32_e32 v211, 0xbe0293ee, v210
	v_fmamk_f32 v82, v82, 0x3e0293ee, v211
	v_fmamk_f32 v83, v83, 0x3e0293ee, v211
	v_fmamk_f32 v84, v84, 0x3e0293ee, v211
	v_fmamk_f32 v85, v85, 0x3e0293ee, v211
	v_fmamk_f32 v86, v86, 0x3e0293ee, v211
	v_fmamk_f32 v87, v87, 0x3e0293ee, v211
	v_fmamk_f32 v88, v88, 0x3e0293ee, v211
	v_fmamk_f32 v89, v89, 0x3e0293ee, v211
	v_fmamk_f32 v90, v90, 0x3e0293ee, v211
	v_fmamk_f32 v91, v91, 0x3e0293ee, v211
	v_fmamk_f32 v92, v92, 0x3e0293ee, v211
	v_fmamk_f32 v93, v93, 0x3e0293ee, v211
	v_fmamk_f32 v94, v94, 0x3e0293ee, v211
	v_fmamk_f32 v95, v95, 0x3e0293ee, v211
	v_fmamk_f32 v96, v96, 0x3e0293ee, v211
	v_fmamk_f32 v97, v97, 0x3e0293ee, v211
	v_exp_f32_e32 v146, v82
	v_exp_f32_e32 v161, v83
	v_exp_f32_e32 v147, v84
	v_exp_f32_e32 v160, v85
	v_exp_f32_e32 v148, v86
	v_exp_f32_e32 v159, v87
	v_exp_f32_e32 v149, v88
	v_exp_f32_e32 v158, v89
	v_exp_f32_e32 v150, v90
	v_exp_f32_e32 v157, v91
	v_exp_f32_e32 v151, v92
	v_exp_f32_e32 v156, v93
	v_exp_f32_e32 v152, v94
	v_exp_f32_e32 v155, v95
	v_exp_f32_e32 v153, v96
	v_exp_f32_e32 v154, v97
	v_fmamk_f32 v220, v66, 0x3e0293ee, v211
	v_fmamk_f32 v221, v67, 0x3e0293ee, v211
	v_fmamk_f32 v222, v68, 0x3e0293ee, v211
	v_fmamk_f32 v223, v69, 0x3e0293ee, v211
	v_fmamk_f32 v224, v70, 0x3e0293ee, v211
	v_fmamk_f32 v213, v71, 0x3e0293ee, v211
	v_fmamk_f32 v214, v72, 0x3e0293ee, v211
	v_fmamk_f32 v215, v73, 0x3e0293ee, v211
	v_fmamk_f32 v216, v74, 0x3e0293ee, v211
	v_fmamk_f32 v217, v75, 0x3e0293ee, v211
	v_fmamk_f32 v218, v76, 0x3e0293ee, v211
	v_fmamk_f32 v219, v77, 0x3e0293ee, v211
	v_fmamk_f32 v212, v78, 0x3e0293ee, v211
	v_fmamk_f32 v225, v79, 0x3e0293ee, v211
	v_fmamk_f32 v226, v80, 0x3e0293ee, v211
	v_fmac_f32_e32 v211, 0x3e0293ee, v81
	v_xor_b32_e32 v177, 0x10000, v177
	v_xor_b32_e32 v194, 0x10000, v194
	v_xor_b32_e32 v195, 0x10000, v195
	v_xor_b32_e32 v196, 0x10000, v196
	s_waitcnt lgkmcnt(0)
	s_barrier
	ds_read_b128 v[66:69], v177 offset:32768
	ds_read_b128 v[70:73], v177 offset:40960
	ds_read_b128 v[232:235], v194 offset:32768
	ds_read_b128 v[236:239], v194 offset:40960
	ds_read_b128 v[240:243], v195 offset:32768
	ds_read_b128 v[244:247], v195 offset:40960
	ds_read_b128 v[248:251], v196 offset:32768
	ds_read_b128 v[114:117], v196 offset:40960
	v_exp_f32_e32 v213, v213
	v_exp_f32_e32 v214, v214
	s_waitcnt lgkmcnt(7)
	v_mfma_f32_32x32x16_bf16 v[82:97], v[66:69], v[102:105], 0
	v_exp_f32_e32 v215, v215
	v_exp_f32_e32 v216, v216
	v_exp_f32_e32 v217, v217
	v_exp_f32_e32 v218, v218
	v_exp_f32_e32 v219, v219
	s_waitcnt lgkmcnt(6)
	v_mfma_f32_32x32x16_bf16 v[66:81], v[70:73], v[102:105], 0
	s_waitcnt lgkmcnt(5)
	v_mfma_f32_32x32x16_bf16 v[82:97], v[232:235], v[98:101], v[82:97]
	s_waitcnt lgkmcnt(4)
	v_mfma_f32_32x32x16_bf16 v[66:81], v[236:239], v[98:101], v[66:81]
	s_waitcnt lgkmcnt(3)
	v_mfma_f32_32x32x16_bf16 v[82:97], v[240:243], v[106:109], v[82:97]
	s_waitcnt lgkmcnt(2)
	v_mfma_f32_32x32x16_bf16 v[66:81], v[244:247], v[106:109], v[66:81]
	s_waitcnt lgkmcnt(1)
	v_mfma_f32_32x32x16_bf16 v[82:97], v[248:251], v[110:113], v[82:97]
	v_exp_f32_e32 v186, v220
	v_exp_f32_e32 v220, v224
	v_exp_f32_e32 v224, v211
	v_add_f32_e32 v211, 0, v146
	v_add_f32_e32 v211, v161, v211
	v_add_f32_e32 v211, v147, v211
	v_add_f32_e32 v211, v160, v211
	v_add_f32_e32 v211, v148, v211
	v_add_f32_e32 v211, v159, v211
	v_add_f32_e32 v211, v149, v211
	v_add_f32_e32 v211, v158, v211
	v_add_f32_e32 v211, v150, v211
	v_add_f32_e32 v211, v157, v211
	v_add_f32_e32 v211, v151, v211
	v_add_f32_e32 v211, v156, v211
	v_add_f32_e32 v211, v152, v211
	v_exp_f32_e32 v187, v221
	v_add_f32_e32 v211, v155, v211
	v_exp_f32_e32 v188, v222
	v_add_f32_e32 v211, v153, v211
	v_exp_f32_e32 v189, v223
	v_add_f32_e32 v211, v154, v211
	v_add_f32_e32 v211, v186, v211
	v_add_f32_e32 v211, v187, v211
	v_add_f32_e32 v211, v188, v211
	v_add_f32_e32 v211, v189, v211
	v_add_f32_e32 v211, v220, v211
	v_add_f32_e32 v211, v213, v211
	v_add_f32_e32 v211, v214, v211
	v_add_f32_e32 v211, v215, v211
	v_exp_f32_e32 v221, v212
	v_add_f32_e32 v211, v216, v211
	v_exp_f32_e32 v222, v225
	v_add_f32_e32 v211, v217, v211
	s_waitcnt lgkmcnt(0)
	v_mfma_f32_32x32x16_bf16 v[66:81], v[114:117], v[110:113], v[66:81]
	v_exp_f32_e32 v223, v226
	v_add_f32_e32 v211, v218, v211
	v_add_f32_e32 v211, v219, v211
	v_add_f32_e32 v211, v221, v211
	v_add_f32_e32 v211, v222, v211
	v_add_f32_e32 v211, v223, v211
	v_add_f32_e32 v211, v224, v211
	v_mov_b32_e32 v212, v211
	v_cvt_pk_bf16_f32 v146, v146, v161
	v_cvt_pk_bf16_f32 v147, v147, v160
	v_cvt_pk_bf16_f32 v148, v148, v159
	v_cvt_pk_bf16_f32 v149, v149, v158
	v_cvt_pk_bf16_f32 v150, v150, v157
	v_cvt_pk_bf16_f32 v151, v151, v156
	v_cvt_pk_bf16_f32 v152, v152, v155
	v_cvt_pk_bf16_f32 v153, v153, v154
	v_cvt_pk_bf16_f32 v154, v186, v187
	v_cvt_pk_bf16_f32 v155, v188, v189
	v_cvt_pk_bf16_f32 v156, v220, v213
	v_cvt_pk_bf16_f32 v157, v214, v215
	v_cvt_pk_bf16_f32 v158, v216, v217
	v_cvt_pk_bf16_f32 v159, v218, v219
	v_cvt_pk_bf16_f32 v160, v221, v222
	v_cvt_pk_bf16_f32 v161, v223, v224
	s_nop 1
	v_permlane32_swap_b32_e32 v211, v212
	v_permlane32_swap_b32_e32 v146, v148
	v_permlane32_swap_b32_e32 v147, v149
	v_permlane32_swap_b32_e32 v150, v152
	v_permlane32_swap_b32_e32 v151, v153
	v_permlane32_swap_b32_e32 v154, v156
	v_permlane32_swap_b32_e32 v155, v157
	v_permlane32_swap_b32_e32 v158, v160
	v_permlane32_swap_b32_e32 v159, v161
	s_waitcnt vmcnt(0)
	ds_write_b128 v192, v[130:133] offset:16384
	ds_write_b128 v193, v[134:137] offset:16384
	ds_write_b128 v190, v[138:141] offset:49152
	ds_write_b128 v191, v[142:145] offset:49152
	s_cmp_gt_u32 s34, 60
	s_cselect_b64 s[2:3], -1, 0
	s_and_b64 vcc, exec, s[2:3]
	s_cbranch_vccnz .LBB0_1028
	v_add_co_u32_e32 v114, vcc, 0x19040000, v168
	s_nop 1
	v_addc_co_u32_e32 v115, vcc, 0, v169, vcc
	v_add_co_u32_e32 v118, vcc, 0x19088000, v168
	s_nop 1
	v_addc_co_u32_e32 v119, vcc, 0, v169, vcc
	v_add_co_u32_e32 v122, vcc, 0x1f660000, v166
	global_load_dwordx4 v[114:117], v[114:115], off
	s_nop 0
	global_load_dwordx4 v[118:121], v[118:119], off
	v_addc_co_u32_e32 v123, vcc, 0, v167, vcc
	v_add_co_u32_e32 v126, vcc, 0x1f66c000, v166
	s_nop 1
	v_addc_co_u32_e32 v127, vcc, 0, v167, vcc
	global_load_dwordx4 v[122:125], v[122:123], off
	s_nop 0
	global_load_dwordx4 v[126:129], v[126:127], off

; #define SWRITE(b, i) do { *(bf16x8*)((char*)V_lds + (b) * SHM_V + vst0) = sr_[i].vs0;          \
;     *(bf16x8*)((char*)V_lds + (b) * SHM_V + vst1) = sr_[i].vs1; int kc = sc * 2;               \
;     *(bf16x8*)((char*)K_lds + (b) * SHM_K + KSWZ(sr, kc)) = sr_[i].ks0;                       \
;     *(bf16x8*)((char*)K_lds + (b) * SHM_K + KSWZ(32 + sr, kc)) = sr_[i].ks1; } while (0)
; #define SWAIT() asm volatile("s_waitcnt vmcnt(4)" ::: "memory")
; #define RESC(a) do { if (__any((a) < 1.f)) { if (hi == 0) al_l[r32] = (a); asm volatile("s_waitcnt lgkmcnt(0)" ::: "memory"); \
;     _Pragma("unroll") for (int d = 0; d < 4; ++d) _Pragma("unroll") for (int r = 0; r < 16; ++r) o[d][r] *= al_l[crow(r, hi)]; } } while (0)
; __device__ __forceinline__ void partialSM(f32x16& p0, f32x16& p1, float& m_reg, float& mn, float& alpha) {
;     ...
;   else { mn = fmaxf(m_reg, pmax); alpha = __builtin_amdgcn_exp2f((m_reg - mn) * C); m_reg = mn; }
;   float mnC = -mn * C;
; #pragma unroll
;   for (int r = 0; r < 16; ++r) p0[r] = fmaf(p0[r], C, mnC);
; #pragma unroll
;   for (int r = 0; r < 16; ++r) p1[r] = fmaf(p1[r], C, mnC);
; #pragma unroll
;   for (int r = 0; r < 16; ++r) p0[r] = __builtin_amdgcn_exp2f(p0[r]);
; template <int DLO, int DHI>
; __device__ __forceinline__ void attn_dense_body(const int g_wave, const bf16* __restrict__ Qb, const bf16* __restrict__ Kh, const bf16* __restrict__ Vh,
;                                                 bf16* __restrict__ Ob, int ldo, char* lds) {
;     ...
;     pv_d0(o, vb0 + (int)SHM_V, pa0, pa1, pa2, pa3); partialSM(pA0, pA1, m_reg, mnA, alA);
;     __syncthreads(); SWAIT(); SWRITE(1, SO);
;     RESC(alA); __syncthreads();
.LBB0_1032:
	v_cndmask_b32_e64 v150, v147, v210, s[8:9]
	v_mul_f32_e32 v136, 0xbe0293ee, v150
	v_mov_b32_e32 v137, v136
	v_fmamk_f32 v82, v82, 0x3e0293ee, v136
	v_fmamk_f32 v83, v83, 0x3e0293ee, v136
	v_fmamk_f32 v84, v84, 0x3e0293ee, v136
	v_fmamk_f32 v85, v85, 0x3e0293ee, v136
	v_fmamk_f32 v86, v86, 0x3e0293ee, v136
	v_fmamk_f32 v87, v87, 0x3e0293ee, v136
	v_fmamk_f32 v88, v88, 0x3e0293ee, v136
	v_fmamk_f32 v89, v89, 0x3e0293ee, v136
	v_fmamk_f32 v90, v90, 0x3e0293ee, v136
	v_fmamk_f32 v91, v91, 0x3e0293ee, v136
	v_fmamk_f32 v92, v92, 0x3e0293ee, v136
	v_fmamk_f32 v93, v93, 0x3e0293ee, v136
	v_fmamk_f32 v94, v94, 0x3e0293ee, v136
	v_fmamk_f32 v95, v95, 0x3e0293ee, v136
	v_fmamk_f32 v96, v96, 0x3e0293ee, v136
	v_fmac_f32_e32 v137, 0x3e0293ee, v97
	v_exp_f32_e32 v161, v82
	v_exp_f32_e32 v167, v83
	v_exp_f32_e32 v147, v84
	v_exp_f32_e32 v166, v85
	v_exp_f32_e32 v148, v86
	v_exp_f32_e32 v160, v87
	v_exp_f32_e32 v149, v88
	v_exp_f32_e32 v159, v89
	v_exp_f32_e32 v156, v90
	v_exp_f32_e32 v158, v91
	v_exp_f32_e32 v154, v92
	v_exp_f32_e32 v157, v93
	v_exp_f32_e32 v152, v94
	v_exp_f32_e32 v155, v95
	v_exp_f32_e32 v151, v96
	v_exp_f32_e32 v153, v137
	v_fma_f32 v142, v66, s62, v136
	v_fma_f32 v143, v67, s62, v136
	v_add_f32_e32 v66, v207, v208
	s_mov_b64 s[4:5], 0x30000
	v_fmac_f32_e32 v66, v197, v174
	v_add_f32_e32 v174, v211, v212
	v_lshl_add_u64 v[162:163], v[162:163], 0, s[4:5]
	s_mov_b64 s[4:5], 0x120000
	v_fma_f32 v140, v68, s62, v136
	v_fma_f32 v141, v69, s62, v136
	v_fma_f32 v134, v70, s62, v136
	v_fma_f32 v135, v71, s62, v136
	v_fma_f32 v132, v72, s62, v136
	v_fma_f32 v133, v73, s62, v136
	v_fma_f32 v130, v74, s62, v136
	v_fma_f32 v131, v75, s62, v136
	v_fma_f32 v144, v76, s62, v136
	v_fma_f32 v145, v77, s62, v136
	v_fma_f32 v138, v78, s62, v136
	v_fma_f32 v139, v79, s62, v136
	v_fma_f32 v137, v81, s62, v136
	v_fma_f32 v136, v80, s62, v136
	v_fmac_f32_e32 v174, v66, v209
	s_add_i32 s34, s34, 2
	v_lshl_add_u64 v[164:165], v[164:165], 0, s[4:5]
	s_and_b64 vcc, exec, s[2:3]
	v_xor_b32_e32 v176, 0x10000, v176
	v_xor_b32_e32 v175, 0x10000, v175
	v_xor_b32_e32 v192, 0x10000, v192
	v_xor_b32_e32 v193, 0x10000, v193
	v_xor_b32_e32 v190, 0x10000, v190
	v_xor_b32_e32 v191, 0x10000, v191
	s_waitcnt lgkmcnt(0)
	s_barrier
	s_cbranch_vccnz .LBB0_1034
	v_mov_b32_e32 v197, v146
	s_branch .LBB0_1022

; #define SBAR() __builtin_amdgcn_sched_barrier(0)
; #define SWRITE(b, i) do { *(bf16x8*)((char*)V_lds + (b) * SHM_V + vst0) = sr_[i].vs0;          \
;     *(bf16x8*)((char*)V_lds + (b) * SHM_V + vst1) = sr_[i].vs1; int kc = sc * 2;               \
;     *(bf16x8*)((char*)K_lds + (b) * SHM_K + KSWZ(sr, kc)) = sr_[i].ks0;                       \
;     *(bf16x8*)((char*)K_lds + (b) * SHM_K + KSWZ(32 + sr, kc)) = sr_[i].ks1; } while (0)
; #define SWAIT() asm volatile("s_waitcnt vmcnt(4)" ::: "memory")
; #define RESC(a) do { if (__any((a) < 1.f)) { if (hi == 0) al_l[r32] = (a); asm volatile("s_waitcnt lgkmcnt(0)" ::: "memory"); \
;     _Pragma("unroll") for (int d = 0; d < 4; ++d) _Pragma("unroll") for (int r = 0; r < 16; ++r) o[d][r] *= al_l[crow(r, hi)]; } } while (0)
; __device__ __forceinline__ void partialSM(f32x16& p0, f32x16& p1, float& m_reg, float& mn, float& alpha) {
;     ...
;   float mnC = -mn * C;
; #pragma unroll
;   for (int r = 0; r < 16; ++r) p0[r] = fmaf(p0[r], C, mnC);
; #pragma unroll
;   for (int r = 0; r < 16; ++r) p1[r] = fmaf(p1[r], C, mnC);
; #pragma unroll
;   for (int r = 0; r < 16; ++r) p0[r] = __builtin_amdgcn_exp2f(p0[r]);
; template <int DLO, int DHI>
; __device__ __forceinline__ void attn_dense_body(const int g_wave, const bf16* __restrict__ Qb, const bf16* __restrict__ Kh, const bf16* __restrict__ Vh,
;                                                 bf16* __restrict__ Ob, int ldo, char* lds) {
;     ...
;     __syncthreads(); SWAIT(); SWRITE(0, SE);
;     RESC(alB); __syncthreads();
;     SBAR(); qkt<DLO, DHI>(pA0, pA1, K_lds, qr, r32, hi);
.LBB0_1047:
	v_cndmask_b32_e64 v230, v162, v170, s[8:9]
	v_mul_f32_e32 v231, 0xbe0293ee, v230
	v_fmamk_f32 v82, v82, 0x3e0293ee, v231
	v_fmamk_f32 v83, v83, 0x3e0293ee, v231
	v_fmamk_f32 v84, v84, 0x3e0293ee, v231
	v_fmamk_f32 v85, v85, 0x3e0293ee, v231
	v_fmamk_f32 v86, v86, 0x3e0293ee, v231
	v_fmamk_f32 v87, v87, 0x3e0293ee, v231
	v_fmamk_f32 v88, v88, 0x3e0293ee, v231
	v_fmamk_f32 v89, v89, 0x3e0293ee, v231
	v_fmamk_f32 v90, v90, 0x3e0293ee, v231
	v_fmamk_f32 v91, v91, 0x3e0293ee, v231
	v_fmamk_f32 v92, v92, 0x3e0293ee, v231
	v_fmamk_f32 v93, v93, 0x3e0293ee, v231
	v_fmamk_f32 v94, v94, 0x3e0293ee, v231
	v_fmamk_f32 v95, v95, 0x3e0293ee, v231
	v_fmamk_f32 v96, v96, 0x3e0293ee, v231
	v_fmamk_f32 v97, v97, 0x3e0293ee, v231
	v_exp_f32_e32 v162, v82
	v_exp_f32_e32 v177, v83
	v_exp_f32_e32 v163, v84
	v_exp_f32_e32 v176, v85
	v_exp_f32_e32 v164, v86
	v_exp_f32_e32 v175, v87
	v_exp_f32_e32 v165, v88
	v_exp_f32_e32 v174, v89
	v_exp_f32_e32 v166, v90
	v_exp_f32_e32 v173, v91
	v_exp_f32_e32 v167, v92
	v_exp_f32_e32 v172, v93
	v_exp_f32_e32 v168, v94
	v_exp_f32_e32 v171, v95
	v_exp_f32_e32 v169, v96
	v_exp_f32_e32 v170, v97
	v_fmamk_f32 v240, v66, 0x3e0293ee, v231
	v_fmamk_f32 v241, v67, 0x3e0293ee, v231
	v_fmamk_f32 v242, v68, 0x3e0293ee, v231
	v_fmamk_f32 v243, v69, 0x3e0293ee, v231
	v_fmamk_f32 v244, v70, 0x3e0293ee, v231
	v_fmamk_f32 v233, v71, 0x3e0293ee, v231
	v_fmamk_f32 v234, v72, 0x3e0293ee, v231
	v_fmamk_f32 v235, v73, 0x3e0293ee, v231
	v_fmamk_f32 v236, v74, 0x3e0293ee, v231
	v_fmamk_f32 v237, v75, 0x3e0293ee, v231
	v_fmamk_f32 v238, v76, 0x3e0293ee, v231
	v_fmamk_f32 v239, v77, 0x3e0293ee, v231
	v_fmamk_f32 v232, v78, 0x3e0293ee, v231
	v_fmamk_f32 v245, v79, 0x3e0293ee, v231
	v_fmamk_f32 v246, v80, 0x3e0293ee, v231
	v_fmac_f32_e32 v231, 0x3e0293ee, v81
	v_xor_b32_e32 v218, 0x10000, v218
	v_xor_b32_e32 v225, 0x10000, v225
	v_xor_b32_e32 v224, 0x10000, v224
	v_xor_b32_e32 v222, 0x10000, v222
	v_xor_b32_e32 v220, 0x10000, v220
	v_xor_b32_e32 v219, 0x10000, v219
	v_xor_b32_e32 v221, 0x10000, v221
	v_xor_b32_e32 v223, 0x10000, v223
	s_waitcnt lgkmcnt(0)
	s_barrier
; #define SBAR() __builtin_amdgcn_sched_barrier(0)
; #define SLOAD(i, k0) do { sr_[i].vs0 = ld8(&Vh[(long)((k0) + sr) * LDV + sc]); sr_[i].vs1 = ld8(&Vh[(long)((k0) + 32 + sr) * LDV + sc]); \
;     sr_[i].ks0 = ld8(&Kh[(long)((k0) + sr) * LDK + sc]); sr_[i].ks1 = ld8(&Kh[(long)((k0) + 32 + sr) * LDK + sc]); } while (0)
; __device__ __forceinline__ void finishSM(f32x16& p0, f32x16& p1, float alpha, float& l_reg, bf16x8& pa0, bf16x8& pa1, bf16x8& pa2, bf16x8& pa3) {
; #pragma unroll
;   for (int r = 0; r < 16; ++r) p1[r] = __builtin_amdgcn_exp2f(p1[r]);
;   float ps = 0;
; #pragma unroll
;   for (int r = 0; r < 16; ++r) ps += p0[r];
; #pragma unroll
;   for (int r = 0; r < 16; ++r) ps += p1[r];
;   { auto rr = __builtin_amdgcn_permlane32_swap(__float_as_uint(ps), __float_as_uint(ps), false, false);
;     ps = __uint_as_float(rr[0]) + __uint_as_float(rr[1]); }
;   l_reg = l_reg * alpha + ps;
;   PK4(p0, 0, pa0); PK4(p0, 8, pa1); PK4(p1, 0, pa2); PK4(p1, 8, pa3);
; }
;   p0 = f32x16{}; p1 = f32x16{};
; #pragma unroll
;   for (int d0 = DLO; d0 < DHI; ++d0) { int cb = (d0 * 16 + hi * 8) * 2;
;     bf16x8 b0 = *reinterpret_cast<const bf16x8*>((const char*)Ks + KSWZ(r32, cb));
;     bf16x8 b1 = *reinterpret_cast<const bf16x8*>((const char*)Ks + KSWZ(32 + r32, cb));
;     p0 = __builtin_amdgcn_mfma_f32_32x32x16_bf16(b0, qr[d0], p0, 0, 0, 0);
;     p1 = __builtin_amdgcn_mfma_f32_32x32x16_bf16(b1, qr[d0], p1, 0, 0, 0); }
; }
; template <int DLO, int DHI>
; __device__ __forceinline__ void attn_dense_body(const int g_wave, const bf16* __restrict__ Qb, const bf16* __restrict__ Kh, const bf16* __restrict__ Vh,
;                                                 bf16* __restrict__ Ob, int ldo, char* lds) {
;     ...
;     SBAR(); qkt<DLO, DHI>(pA0, pA1, K_lds, qr, r32, hi);
;     finishSM(pB0, pB1, alB, l_reg, pa0, pa1, pa2, pa3); SBAR();
;     if (j + 3 < NT) SLOAD(SE, (j + 3) * KVBLK); SBAR();
	ds_read_b128 v[66:69], v218 offset:32768
	ds_read_b128 v[70:73], v218 offset:40960
	ds_read_b128 v[130:133], v225 offset:32768
	ds_read_b128 v[134:137], v225 offset:40960
	ds_read_b128 v[138:141], v224 offset:32768
	ds_read_b128 v[142:145], v224 offset:40960
	v_exp_f32_e32 v233, v233
	v_exp_f32_e32 v234, v234
	s_waitcnt lgkmcnt(5)
	v_mfma_f32_32x32x16_bf16 v[82:97], v[66:69], v[118:121], 0
	v_exp_f32_e32 v235, v235
	v_exp_f32_e32 v236, v236
	v_exp_f32_e32 v237, v237
	v_exp_f32_e32 v238, v238
	v_exp_f32_e32 v239, v239
	s_waitcnt lgkmcnt(4)
	v_mfma_f32_32x32x16_bf16 v[66:81], v[70:73], v[118:121], 0
	s_waitcnt lgkmcnt(3)
	v_mfma_f32_32x32x16_bf16 v[82:97], v[130:133], v[110:113], v[82:97]
	s_waitcnt lgkmcnt(2)
	v_mfma_f32_32x32x16_bf16 v[66:81], v[134:137], v[110:113], v[66:81]
	ds_read_b128 v[130:133], v222 offset:32768
	ds_read_b128 v[134:137], v222 offset:40960
	s_waitcnt lgkmcnt(3)
	v_mfma_f32_32x32x16_bf16 v[82:97], v[138:141], v[126:129], v[82:97]
	s_waitcnt lgkmcnt(2)
	v_mfma_f32_32x32x16_bf16 v[66:81], v[142:145], v[126:129], v[66:81]
	ds_read_b128 v[138:141], v220 offset:32768
	ds_read_b128 v[142:145], v220 offset:40960
	s_waitcnt lgkmcnt(3)
	v_mfma_f32_32x32x16_bf16 v[82:97], v[130:133], v[122:125], v[82:97]
	s_waitcnt lgkmcnt(2)
	v_mfma_f32_32x32x16_bf16 v[66:81], v[134:137], v[122:125], v[66:81]
	ds_read_b128 v[130:133], v219 offset:32768
	ds_read_b128 v[134:137], v219 offset:40960
	s_waitcnt lgkmcnt(3)
	v_mfma_f32_32x32x16_bf16 v[82:97], v[138:141], v[114:117], v[82:97]
	s_waitcnt lgkmcnt(2)
	v_mfma_f32_32x32x16_bf16 v[66:81], v[142:145], v[114:117], v[66:81]
	ds_read_b128 v[138:141], v221 offset:32768
	ds_read_b128 v[142:145], v221 offset:40960
	s_waitcnt lgkmcnt(3)
	v_mfma_f32_32x32x16_bf16 v[82:97], v[130:133], v[106:109], v[82:97]
	s_waitcnt lgkmcnt(2)
	v_mfma_f32_32x32x16_bf16 v[66:81], v[134:137], v[106:109], v[66:81]
	ds_read_b128 v[130:133], v223 offset:32768
	ds_read_b128 v[134:137], v223 offset:40960
	s_waitcnt lgkmcnt(3)
	v_mfma_f32_32x32x16_bf16 v[82:97], v[138:141], v[102:105], v[82:97]
	s_waitcnt lgkmcnt(2)
	v_mfma_f32_32x32x16_bf16 v[66:81], v[142:145], v[102:105], v[66:81]
	s_waitcnt lgkmcnt(1)
	v_mfma_f32_32x32x16_bf16 v[82:97], v[130:133], v[98:101], v[82:97]
	v_exp_f32_e32 v186, v240
	v_exp_f32_e32 v240, v244
	v_exp_f32_e32 v244, v231
	v_add_f32_e32 v231, 0, v162
	v_add_f32_e32 v231, v177, v231
	v_add_f32_e32 v231, v163, v231
	v_add_f32_e32 v231, v176, v231
	v_add_f32_e32 v231, v164, v231
	v_add_f32_e32 v231, v175, v231
	v_add_f32_e32 v231, v165, v231
	v_add_f32_e32 v231, v174, v231
	v_add_f32_e32 v231, v166, v231
	v_add_f32_e32 v231, v173, v231
	v_add_f32_e32 v231, v167, v231
	v_add_f32_e32 v231, v172, v231
	v_add_f32_e32 v231, v168, v231
	v_exp_f32_e32 v187, v241
	v_add_f32_e32 v231, v171, v231
	v_exp_f32_e32 v188, v242
	v_add_f32_e32 v231, v169, v231
	v_exp_f32_e32 v189, v243
	v_add_f32_e32 v231, v170, v231
	v_add_f32_e32 v231, v186, v231
	v_add_f32_e32 v231, v187, v231
	v_add_f32_e32 v231, v188, v231
	v_add_f32_e32 v231, v189, v231
	v_add_f32_e32 v231, v240, v231
	v_add_f32_e32 v231, v233, v231
	v_add_f32_e32 v231, v234, v231
	v_add_f32_e32 v231, v235, v231
	v_exp_f32_e32 v241, v232
	v_add_f32_e32 v231, v236, v231
	v_exp_f32_e32 v242, v245
	v_add_f32_e32 v231, v237, v231
	s_waitcnt lgkmcnt(0)
	v_mfma_f32_32x32x16_bf16 v[66:81], v[134:137], v[98:101], v[66:81]
	v_exp_f32_e32 v243, v246
	v_add_f32_e32 v231, v238, v231
	v_add_f32_e32 v231, v239, v231
	v_add_f32_e32 v231, v241, v231
	v_add_f32_e32 v231, v242, v231
	v_add_f32_e32 v231, v243, v231
	v_add_f32_e32 v231, v244, v231
	v_mov_b32_e32 v232, v231
	v_cvt_pk_bf16_f32 v162, v162, v177
	v_cvt_pk_bf16_f32 v163, v163, v176
	v_cvt_pk_bf16_f32 v164, v164, v175
	v_cvt_pk_bf16_f32 v165, v165, v174
	v_cvt_pk_bf16_f32 v166, v166, v173
	v_cvt_pk_bf16_f32 v167, v167, v172
	v_cvt_pk_bf16_f32 v168, v168, v171
	v_cvt_pk_bf16_f32 v169, v169, v170
	v_cvt_pk_bf16_f32 v170, v186, v187
	v_cvt_pk_bf16_f32 v171, v188, v189
	v_cvt_pk_bf16_f32 v172, v240, v233
	v_cvt_pk_bf16_f32 v173, v234, v235
	v_cvt_pk_bf16_f32 v174, v236, v237
	v_cvt_pk_bf16_f32 v175, v238, v239
	v_cvt_pk_bf16_f32 v176, v241, v242
	v_cvt_pk_bf16_f32 v177, v243, v244
	s_nop 1
	v_permlane32_swap_b32_e32 v231, v232
	v_permlane32_swap_b32_e32 v162, v164
	v_permlane32_swap_b32_e32 v163, v165
	v_permlane32_swap_b32_e32 v166, v168
	v_permlane32_swap_b32_e32 v167, v169
	v_permlane32_swap_b32_e32 v170, v172
	v_permlane32_swap_b32_e32 v171, v173
	v_permlane32_swap_b32_e32 v174, v176
	v_permlane32_swap_b32_e32 v175, v177
	s_waitcnt vmcnt(0)
	ds_write_b128 v216, v[146:149] offset:16384
	ds_write_b128 v217, v[150:153] offset:16384
	ds_write_b128 v214, v[154:157] offset:49152
	ds_write_b128 v215, v[158:161] offset:49152
	s_cmp_gt_u32 s34, 60
	s_cselect_b64 s[2:3], -1, 0
	s_and_b64 vcc, exec, s[2:3]
	s_cbranch_vccnz .LBB0_1049
	v_add_co_u32_e32 v130, vcc, 0x19040000, v196
	s_nop 1
	v_addc_co_u32_e32 v131, vcc, 0, v197, vcc
	v_add_co_u32_e32 v134, vcc, 0x19088000, v196
	s_nop 1
	v_addc_co_u32_e32 v135, vcc, 0, v197, vcc
	v_add_co_u32_e32 v138, vcc, 0x1f660000, v194
	global_load_dwordx4 v[130:133], v[130:131], off
	s_nop 0
	global_load_dwordx4 v[134:137], v[134:135], off
	v_addc_co_u32_e32 v139, vcc, 0, v195, vcc
	v_add_co_u32_e32 v142, vcc, 0x1f66c000, v194
	s_nop 1
	v_addc_co_u32_e32 v143, vcc, 0, v195, vcc
	global_load_dwordx4 v[138:141], v[138:139], off
	s_nop 0
	global_load_dwordx4 v[142:145], v[142:143], off

; #define SWRITE(b, i) do { *(bf16x8*)((char*)V_lds + (b) * SHM_V + vst0) = sr_[i].vs0;          \
;     *(bf16x8*)((char*)V_lds + (b) * SHM_V + vst1) = sr_[i].vs1; int kc = sc * 2;               \
;     *(bf16x8*)((char*)K_lds + (b) * SHM_K + KSWZ(sr, kc)) = sr_[i].ks0;                       \
;     *(bf16x8*)((char*)K_lds + (b) * SHM_K + KSWZ(32 + sr, kc)) = sr_[i].ks1; } while (0)
; #define SWAIT() asm volatile("s_waitcnt vmcnt(4)" ::: "memory")
; #define RESC(a) do { if (__any((a) < 1.f)) { if (hi == 0) al_l[r32] = (a); asm volatile("s_waitcnt lgkmcnt(0)" ::: "memory"); \
;     _Pragma("unroll") for (int d = 0; d < 4; ++d) _Pragma("unroll") for (int r = 0; r < 16; ++r) o[d][r] *= al_l[crow(r, hi)]; } } while (0)
; __device__ __forceinline__ void partialSM(f32x16& p0, f32x16& p1, float& m_reg, float& mn, float& alpha) {
;     ...
;   else { mn = fmaxf(m_reg, pmax); alpha = __builtin_amdgcn_exp2f((m_reg - mn) * C); m_reg = mn; }
;   float mnC = -mn * C;
; #pragma unroll
;   for (int r = 0; r < 16; ++r) p0[r] = fmaf(p0[r], C, mnC);
; #pragma unroll
;   for (int r = 0; r < 16; ++r) p1[r] = fmaf(p1[r], C, mnC);
; #pragma unroll
;   for (int r = 0; r < 16; ++r) p0[r] = __builtin_amdgcn_exp2f(p0[r]);
; template <int DLO, int DHI>
; __device__ __forceinline__ void attn_dense_body(const int g_wave, const bf16* __restrict__ Qb, const bf16* __restrict__ Kh, const bf16* __restrict__ Vh,
;                                                 bf16* __restrict__ Ob, int ldo, char* lds) {
;     ...
;     pv_d0(o, vb0 + (int)SHM_V, pa0, pa1, pa2, pa3); partialSM(pA0, pA1, m_reg, mnA, alA);
;     __syncthreads(); SWAIT(); SWRITE(1, SO);
;     RESC(alA); __syncthreads();
.LBB0_1053:
	v_cndmask_b32_e64 v170, v163, v230, s[8:9]
	v_mul_f32_e32 v152, 0xbe0293ee, v170
	v_mov_b32_e32 v153, v152
	v_fmamk_f32 v82, v82, 0x3e0293ee, v152
	v_fmamk_f32 v83, v83, 0x3e0293ee, v152
	v_fmamk_f32 v84, v84, 0x3e0293ee, v152
	v_fmamk_f32 v85, v85, 0x3e0293ee, v152
	v_fmamk_f32 v86, v86, 0x3e0293ee, v152
	v_fmamk_f32 v87, v87, 0x3e0293ee, v152
	v_fmamk_f32 v88, v88, 0x3e0293ee, v152
	v_fmamk_f32 v89, v89, 0x3e0293ee, v152
	v_fmamk_f32 v90, v90, 0x3e0293ee, v152
	v_fmamk_f32 v91, v91, 0x3e0293ee, v152
	v_fmamk_f32 v92, v92, 0x3e0293ee, v152
	v_fmamk_f32 v93, v93, 0x3e0293ee, v152
	v_fmamk_f32 v94, v94, 0x3e0293ee, v152
	v_fmamk_f32 v95, v95, 0x3e0293ee, v152
	v_fmamk_f32 v96, v96, 0x3e0293ee, v152
	v_fmac_f32_e32 v153, 0x3e0293ee, v97
	v_exp_f32_e32 v177, v82
	v_exp_f32_e32 v195, v83
	v_exp_f32_e32 v163, v84
	v_exp_f32_e32 v194, v85
	v_exp_f32_e32 v164, v86
	v_exp_f32_e32 v176, v87
	v_exp_f32_e32 v165, v88
	v_exp_f32_e32 v175, v89
	v_exp_f32_e32 v166, v90
	v_exp_f32_e32 v174, v91
	v_exp_f32_e32 v167, v92
	v_exp_f32_e32 v173, v93
	v_exp_f32_e32 v168, v94
	v_exp_f32_e32 v172, v95
	v_exp_f32_e32 v169, v96
	v_exp_f32_e32 v171, v153
	v_fma_f32 v158, v66, s62, v152
	v_fma_f32 v159, v67, s62, v152
	v_add_f32_e32 v66, v227, v228
	s_mov_b64 s[4:5], 0x30000
	v_fmac_f32_e32 v66, v226, v211
	v_add_f32_e32 v211, v231, v232
	v_lshl_add_u64 v[190:191], v[190:191], 0, s[4:5]
	s_mov_b64 s[4:5], 0x120000
	v_fma_f32 v156, v68, s62, v152
	v_fma_f32 v157, v69, s62, v152
	v_fma_f32 v150, v70, s62, v152
	v_fma_f32 v151, v71, s62, v152
	v_fma_f32 v148, v72, s62, v152
	v_fma_f32 v149, v73, s62, v152
	v_fma_f32 v146, v74, s62, v152
	v_fma_f32 v147, v75, s62, v152
	v_fma_f32 v160, v76, s62, v152
	v_fma_f32 v161, v77, s62, v152
	v_fma_f32 v154, v78, s62, v152
	v_fma_f32 v155, v79, s62, v152
	v_fma_f32 v153, v81, s62, v152
	v_fma_f32 v152, v80, s62, v152
	v_fmac_f32_e32 v211, v66, v229
	s_add_i32 s34, s34, 2
	v_lshl_add_u64 v[192:193], v[192:193], 0, s[4:5]
	s_and_b64 vcc, exec, s[2:3]
	v_xor_b32_e32 v213, 0x10000, v213
	v_xor_b32_e32 v212, 0x10000, v212
	v_xor_b32_e32 v216, 0x10000, v216
	v_xor_b32_e32 v217, 0x10000, v217
	v_xor_b32_e32 v214, 0x10000, v214
	v_xor_b32_e32 v215, 0x10000, v215
	s_waitcnt lgkmcnt(0)
	s_barrier
	s_cbranch_vccnz .LBB0_1055
	v_mov_b32_e32 v226, v162
	s_branch .LBB0_1043
